# layer-1 out-proj epilogue rewritten: residual loads 16 ahead, lanes exchange acc halves (DPP) so each load/store covers full 128B lines
# speedup vs baseline: 1.0442x; 1.0442x over previous
; #define LAS __attribute__((address_space(3)))
;     __device__ __forceinline__ void operator()(const f32x4 (&acc)[2][2][4][2], const Unit& u, int wr, int wc, int fr, int fq, LAS unsigned char*) const {
;         const int row0 = u.pm * BM + wr * 64 + fr; const int col0 = u.pn * BM + wc * 32 + 8 * fq;
; #pragma unroll
;         for (int ai = 0; ai < 2; ++ai)
; #pragma unroll
;             for (int m = 0; m < 4; ++m) { const size_t ro = (size_t)(row0 + ai * HALF + m * 16) * ldc + col0;
; #pragma unroll
;                 for (int bj = 0; bj < 2; ++bj) { const size_t o = ro + bj * HALF; const f32x4 r0 = *(const f32x4*)(res + o), r1 = *(const f32x4*)(res + o + 4);
;                     *(f32x4*)(O + o) = r0 + acc[ai][bj][m][0]; *(f32x4*)(O + o + 4) = r1 + acc[ai][bj][m][1]; } }
;     }
.LBB0_762:
	v_and_b32_e32 v176, 8, v140
	v_sub_u32_e32 v166, v140, v176
	v_lshl_add_u32 v166, s39, 8, v166
	v_mov_b32_e32 v167, 0
	v_lshlrev_b64 v[138:139], 12, v[166:167]
	v_lshl_add_u64 v[138:139], s[76:77], 0, v[138:139]
	v_lshl_or_b32 v166, s5, 8, v142
	v_lshlrev_b32_e32 v166, 2, v166
	v_lshl_add_u32 v166, v176, 1, v166
	v_lshl_add_u64 v[138:139], v[138:139], 0, v[166:167]
	s_mov_b64 s[16:17], 0x8000
	s_mov_b64 s[18:19], 0x10000
	s_mov_b64 s[40:41], 0x50000
	v_lshl_add_u64 v[160:161], v[138:139], 0, s[16:17]
	v_mov_b64_e32 v[162:163], v[138:139]
	v_mov_b64_e32 v[164:165], v[160:161]
	global_load_dwordx4 v[196:199], v[138:139], off
	global_load_dwordx4 v[200:203], v[138:139], off offset:512
	global_load_dwordx4 v[204:207], v[160:161], off
	global_load_dwordx4 v[208:211], v[160:161], off offset:512
	v_lshl_add_u64 v[138:139], v[138:139], 0, s[18:19]
	v_lshl_add_u64 v[160:161], v[160:161], 0, s[18:19]
	global_load_dwordx4 v[212:215], v[138:139], off
	global_load_dwordx4 v[216:219], v[138:139], off offset:512
	global_load_dwordx4 v[220:223], v[160:161], off
	global_load_dwordx4 v[224:227], v[160:161], off offset:512
	v_lshl_add_u64 v[138:139], v[138:139], 0, s[18:19]
	v_lshl_add_u64 v[160:161], v[160:161], 0, s[18:19]
	global_load_dwordx4 v[228:231], v[138:139], off
	global_load_dwordx4 v[232:235], v[138:139], off offset:512
	global_load_dwordx4 v[236:239], v[160:161], off
	global_load_dwordx4 v[240:243], v[160:161], off offset:512
	v_lshl_add_u64 v[138:139], v[138:139], 0, s[18:19]
	v_lshl_add_u64 v[160:161], v[160:161], 0, s[18:19]
	global_load_dwordx4 v[168:171], v[138:139], off
	global_load_dwordx4 v[172:175], v[138:139], off offset:512
	global_load_dwordx4 v[180:183], v[160:161], off
	global_load_dwordx4 v[156:159], v[160:161], off offset:512
	v_lshl_add_u64 v[138:139], v[138:139], 0, s[40:41]
	v_lshl_add_u64 v[160:161], v[160:161], 0, s[40:41]
	v_mov_b32_dpp v176, v124 row_ror:8 row_mask:0xf bank_mask:0xf
	v_mov_b32_dpp v177, v125 row_ror:8 row_mask:0xf bank_mask:0xf
	v_mov_b32_dpp v124, v120 row_ror:8 row_mask:0xf bank_mask:0xc
	v_mov_b32_dpp v125, v121 row_ror:8 row_mask:0xf bank_mask:0xc
	v_mov_b32_dpp v120, v176 quad_perm:[0,1,2,3] row_mask:0xf bank_mask:0x3
	v_mov_b32_dpp v121, v177 quad_perm:[0,1,2,3] row_mask:0xf bank_mask:0x3
	v_mov_b32_dpp v176, v126 row_ror:8 row_mask:0xf bank_mask:0xf
	v_mov_b32_dpp v177, v127 row_ror:8 row_mask:0xf bank_mask:0xf
	v_mov_b32_dpp v126, v122 row_ror:8 row_mask:0xf bank_mask:0xc
	v_mov_b32_dpp v127, v123 row_ror:8 row_mask:0xf bank_mask:0xc
	v_mov_b32_dpp v122, v176 quad_perm:[0,1,2,3] row_mask:0xf bank_mask:0x3
	v_mov_b32_dpp v123, v177 quad_perm:[0,1,2,3] row_mask:0xf bank_mask:0x3
	v_mov_b32_dpp v176, v116 row_ror:8 row_mask:0xf bank_mask:0xf
	v_mov_b32_dpp v177, v117 row_ror:8 row_mask:0xf bank_mask:0xf
	v_mov_b32_dpp v116, v112 row_ror:8 row_mask:0xf bank_mask:0xc
	v_mov_b32_dpp v117, v113 row_ror:8 row_mask:0xf bank_mask:0xc
	v_mov_b32_dpp v112, v176 quad_perm:[0,1,2,3] row_mask:0xf bank_mask:0x3
	v_mov_b32_dpp v113, v177 quad_perm:[0,1,2,3] row_mask:0xf bank_mask:0x3
	v_mov_b32_dpp v176, v118 row_ror:8 row_mask:0xf bank_mask:0xf
	v_mov_b32_dpp v177, v119 row_ror:8 row_mask:0xf bank_mask:0xf
	v_mov_b32_dpp v118, v114 row_ror:8 row_mask:0xf bank_mask:0xc
	v_mov_b32_dpp v119, v115 row_ror:8 row_mask:0xf bank_mask:0xc
	v_mov_b32_dpp v114, v176 quad_perm:[0,1,2,3] row_mask:0xf bank_mask:0x3
	v_mov_b32_dpp v115, v177 quad_perm:[0,1,2,3] row_mask:0xf bank_mask:0x3
	v_mov_b32_dpp v176, v108 row_ror:8 row_mask:0xf bank_mask:0xf
	v_mov_b32_dpp v177, v109 row_ror:8 row_mask:0xf bank_mask:0xf
	v_mov_b32_dpp v108, v104 row_ror:8 row_mask:0xf bank_mask:0xc
	v_mov_b32_dpp v109, v105 row_ror:8 row_mask:0xf bank_mask:0xc
	v_mov_b32_dpp v104, v176 quad_perm:[0,1,2,3] row_mask:0xf bank_mask:0x3
	v_mov_b32_dpp v105, v177 quad_perm:[0,1,2,3] row_mask:0xf bank_mask:0x3
	v_mov_b32_dpp v176, v110 row_ror:8 row_mask:0xf bank_mask:0xf
	v_mov_b32_dpp v177, v111 row_ror:8 row_mask:0xf bank_mask:0xf
	v_mov_b32_dpp v110, v106 row_ror:8 row_mask:0xf bank_mask:0xc
	v_mov_b32_dpp v111, v107 row_ror:8 row_mask:0xf bank_mask:0xc
	v_mov_b32_dpp v106, v176 quad_perm:[0,1,2,3] row_mask:0xf bank_mask:0x3
	v_mov_b32_dpp v107, v177 quad_perm:[0,1,2,3] row_mask:0xf bank_mask:0x3
	v_mov_b32_dpp v176, v92 row_ror:8 row_mask:0xf bank_mask:0xf
	v_mov_b32_dpp v177, v93 row_ror:8 row_mask:0xf bank_mask:0xf
	v_mov_b32_dpp v92, v88 row_ror:8 row_mask:0xf bank_mask:0xc
	v_mov_b32_dpp v93, v89 row_ror:8 row_mask:0xf bank_mask:0xc
	v_mov_b32_dpp v88, v176 quad_perm:[0,1,2,3] row_mask:0xf bank_mask:0x3
	v_mov_b32_dpp v89, v177 quad_perm:[0,1,2,3] row_mask:0xf bank_mask:0x3
	v_mov_b32_dpp v176, v94 row_ror:8 row_mask:0xf bank_mask:0xf
	v_mov_b32_dpp v177, v95 row_ror:8 row_mask:0xf bank_mask:0xf
	v_mov_b32_dpp v94, v90 row_ror:8 row_mask:0xf bank_mask:0xc
	v_mov_b32_dpp v95, v91 row_ror:8 row_mask:0xf bank_mask:0xc
	v_mov_b32_dpp v90, v176 quad_perm:[0,1,2,3] row_mask:0xf bank_mask:0x3
	v_mov_b32_dpp v91, v177 quad_perm:[0,1,2,3] row_mask:0xf bank_mask:0x3
	v_mov_b32_dpp v176, v100 row_ror:8 row_mask:0xf bank_mask:0xf
	v_mov_b32_dpp v177, v101 row_ror:8 row_mask:0xf bank_mask:0xf
	v_mov_b32_dpp v100, v96 row_ror:8 row_mask:0xf bank_mask:0xc
	v_mov_b32_dpp v101, v97 row_ror:8 row_mask:0xf bank_mask:0xc
	v_mov_b32_dpp v96, v176 quad_perm:[0,1,2,3] row_mask:0xf bank_mask:0x3
	v_mov_b32_dpp v97, v177 quad_perm:[0,1,2,3] row_mask:0xf bank_mask:0x3
	v_mov_b32_dpp v176, v102 row_ror:8 row_mask:0xf bank_mask:0xf
	v_mov_b32_dpp v177, v103 row_ror:8 row_mask:0xf bank_mask:0xf
	v_mov_b32_dpp v102, v98 row_ror:8 row_mask:0xf bank_mask:0xc
;     __device__ __forceinline__ void operator()(const f32x4 (&acc)[2][2][4][2], const Unit& u, int wr, int wc, int fr, int fq, LAS unsigned char*) const {
;     ...
;             for (int m = 0; m < 4; ++m) { const size_t ro = (size_t)(row0 + ai * HALF + m * 16) * ldc + col0;
; #pragma unroll
;                 for (int bj = 0; bj < 2; ++bj) { const size_t o = ro + bj * HALF; const f32x4 r0 = *(const f32x4*)(res + o), r1 = *(const f32x4*)(res + o + 4);
;                     *(f32x4*)(O + o) = r0 + acc[ai][bj][m][0]; *(f32x4*)(O + o + 4) = r1 + acc[ai][bj][m][1]; } }
	v_mov_b32_dpp v103, v99 row_ror:8 row_mask:0xf bank_mask:0xc
	v_mov_b32_dpp v98, v176 quad_perm:[0,1,2,3] row_mask:0xf bank_mask:0x3
	v_mov_b32_dpp v99, v177 quad_perm:[0,1,2,3] row_mask:0xf bank_mask:0x3
	v_mov_b32_dpp v176, v76 row_ror:8 row_mask:0xf bank_mask:0xf
	v_mov_b32_dpp v177, v77 row_ror:8 row_mask:0xf bank_mask:0xf
	v_mov_b32_dpp v76, v72 row_ror:8 row_mask:0xf bank_mask:0xc
	v_mov_b32_dpp v77, v73 row_ror:8 row_mask:0xf bank_mask:0xc
	v_mov_b32_dpp v72, v176 quad_perm:[0,1,2,3] row_mask:0xf bank_mask:0x3
	v_mov_b32_dpp v73, v177 quad_perm:[0,1,2,3] row_mask:0xf bank_mask:0x3
	v_mov_b32_dpp v176, v78 row_ror:8 row_mask:0xf bank_mask:0xf
	v_mov_b32_dpp v177, v79 row_ror:8 row_mask:0xf bank_mask:0xf
	v_mov_b32_dpp v78, v74 row_ror:8 row_mask:0xf bank_mask:0xc
	v_mov_b32_dpp v79, v75 row_ror:8 row_mask:0xf bank_mask:0xc
	v_mov_b32_dpp v74, v176 quad_perm:[0,1,2,3] row_mask:0xf bank_mask:0x3
	v_mov_b32_dpp v75, v177 quad_perm:[0,1,2,3] row_mask:0xf bank_mask:0x3
	v_mov_b32_dpp v176, v84 row_ror:8 row_mask:0xf bank_mask:0xf
	v_mov_b32_dpp v177, v85 row_ror:8 row_mask:0xf bank_mask:0xf
	v_mov_b32_dpp v84, v80 row_ror:8 row_mask:0xf bank_mask:0xc
	v_mov_b32_dpp v85, v81 row_ror:8 row_mask:0xf bank_mask:0xc
	v_mov_b32_dpp v80, v176 quad_perm:[0,1,2,3] row_mask:0xf bank_mask:0x3
	v_mov_b32_dpp v81, v177 quad_perm:[0,1,2,3] row_mask:0xf bank_mask:0x3
	v_mov_b32_dpp v176, v86 row_ror:8 row_mask:0xf bank_mask:0xf
	v_mov_b32_dpp v177, v87 row_ror:8 row_mask:0xf bank_mask:0xf
	v_mov_b32_dpp v86, v82 row_ror:8 row_mask:0xf bank_mask:0xc
	v_mov_b32_dpp v87, v83 row_ror:8 row_mask:0xf bank_mask:0xc
	v_mov_b32_dpp v82, v176 quad_perm:[0,1,2,3] row_mask:0xf bank_mask:0x3
	v_mov_b32_dpp v83, v177 quad_perm:[0,1,2,3] row_mask:0xf bank_mask:0x3
	v_mov_b32_dpp v176, v68 row_ror:8 row_mask:0xf bank_mask:0xf
	v_mov_b32_dpp v177, v69 row_ror:8 row_mask:0xf bank_mask:0xf
	v_mov_b32_dpp v68, v64 row_ror:8 row_mask:0xf bank_mask:0xc
	v_mov_b32_dpp v69, v65 row_ror:8 row_mask:0xf bank_mask:0xc
	v_mov_b32_dpp v64, v176 quad_perm:[0,1,2,3] row_mask:0xf bank_mask:0x3
	v_mov_b32_dpp v65, v177 quad_perm:[0,1,2,3] row_mask:0xf bank_mask:0x3
	v_mov_b32_dpp v176, v70 row_ror:8 row_mask:0xf bank_mask:0xf
	v_mov_b32_dpp v177, v71 row_ror:8 row_mask:0xf bank_mask:0xf
	v_mov_b32_dpp v70, v66 row_ror:8 row_mask:0xf bank_mask:0xc
	v_mov_b32_dpp v71, v67 row_ror:8 row_mask:0xf bank_mask:0xc
	v_mov_b32_dpp v66, v176 quad_perm:[0,1,2,3] row_mask:0xf bank_mask:0x3
	v_mov_b32_dpp v67, v177 quad_perm:[0,1,2,3] row_mask:0xf bank_mask:0x3
	v_mov_b32_dpp v176, v60 row_ror:8 row_mask:0xf bank_mask:0xf
	v_mov_b32_dpp v177, v61 row_ror:8 row_mask:0xf bank_mask:0xf
	v_mov_b32_dpp v60, v56 row_ror:8 row_mask:0xf bank_mask:0xc
	v_mov_b32_dpp v61, v57 row_ror:8 row_mask:0xf bank_mask:0xc
	v_mov_b32_dpp v56, v176 quad_perm:[0,1,2,3] row_mask:0xf bank_mask:0x3
	v_mov_b32_dpp v57, v177 quad_perm:[0,1,2,3] row_mask:0xf bank_mask:0x3
	v_mov_b32_dpp v176, v62 row_ror:8 row_mask:0xf bank_mask:0xf
	v_mov_b32_dpp v177, v63 row_ror:8 row_mask:0xf bank_mask:0xf
	v_mov_b32_dpp v62, v58 row_ror:8 row_mask:0xf bank_mask:0xc
	v_mov_b32_dpp v63, v59 row_ror:8 row_mask:0xf bank_mask:0xc
	v_mov_b32_dpp v58, v176 quad_perm:[0,1,2,3] row_mask:0xf bank_mask:0x3
	v_mov_b32_dpp v59, v177 quad_perm:[0,1,2,3] row_mask:0xf bank_mask:0x3
	v_mov_b32_dpp v176, v52 row_ror:8 row_mask:0xf bank_mask:0xf
	v_mov_b32_dpp v177, v53 row_ror:8 row_mask:0xf bank_mask:0xf
	v_mov_b32_dpp v52, v48 row_ror:8 row_mask:0xf bank_mask:0xc
	v_mov_b32_dpp v53, v49 row_ror:8 row_mask:0xf bank_mask:0xc
	v_mov_b32_dpp v48, v176 quad_perm:[0,1,2,3] row_mask:0xf bank_mask:0x3
	v_mov_b32_dpp v49, v177 quad_perm:[0,1,2,3] row_mask:0xf bank_mask:0x3
	v_mov_b32_dpp v176, v54 row_ror:8 row_mask:0xf bank_mask:0xf
	v_mov_b32_dpp v177, v55 row_ror:8 row_mask:0xf bank_mask:0xf
	v_mov_b32_dpp v54, v50 row_ror:8 row_mask:0xf bank_mask:0xc
	v_mov_b32_dpp v55, v51 row_ror:8 row_mask:0xf bank_mask:0xc
	v_mov_b32_dpp v50, v176 quad_perm:[0,1,2,3] row_mask:0xf bank_mask:0x3
	v_mov_b32_dpp v51, v177 quad_perm:[0,1,2,3] row_mask:0xf bank_mask:0x3
	v_mov_b32_dpp v176, v44 row_ror:8 row_mask:0xf bank_mask:0xf
	v_mov_b32_dpp v177, v45 row_ror:8 row_mask:0xf bank_mask:0xf
	v_mov_b32_dpp v44, v40 row_ror:8 row_mask:0xf bank_mask:0xc
	v_mov_b32_dpp v45, v41 row_ror:8 row_mask:0xf bank_mask:0xc
	v_mov_b32_dpp v40, v176 quad_perm:[0,1,2,3] row_mask:0xf bank_mask:0x3
	v_mov_b32_dpp v41, v177 quad_perm:[0,1,2,3] row_mask:0xf bank_mask:0x3
	v_mov_b32_dpp v176, v46 row_ror:8 row_mask:0xf bank_mask:0xf
	v_mov_b32_dpp v177, v47 row_ror:8 row_mask:0xf bank_mask:0xf
	v_mov_b32_dpp v46, v42 row_ror:8 row_mask:0xf bank_mask:0xc
	v_mov_b32_dpp v47, v43 row_ror:8 row_mask:0xf bank_mask:0xc
	v_mov_b32_dpp v42, v176 quad_perm:[0,1,2,3] row_mask:0xf bank_mask:0x3
	v_mov_b32_dpp v43, v177 quad_perm:[0,1,2,3] row_mask:0xf bank_mask:0x3
	v_mov_b32_dpp v176, v36 row_ror:8 row_mask:0xf bank_mask:0xf
	v_mov_b32_dpp v177, v37 row_ror:8 row_mask:0xf bank_mask:0xf
	v_mov_b32_dpp v36, v32 row_ror:8 row_mask:0xf bank_mask:0xc
	v_mov_b32_dpp v37, v33 row_ror:8 row_mask:0xf bank_mask:0xc
	v_mov_b32_dpp v32, v176 quad_perm:[0,1,2,3] row_mask:0xf bank_mask:0x3
	v_mov_b32_dpp v33, v177 quad_perm:[0,1,2,3] row_mask:0xf bank_mask:0x3
	v_mov_b32_dpp v176, v38 row_ror:8 row_mask:0xf bank_mask:0xf
	v_mov_b32_dpp v177, v39 row_ror:8 row_mask:0xf bank_mask:0xf
	v_mov_b32_dpp v38, v34 row_ror:8 row_mask:0xf bank_mask:0xc
	v_mov_b32_dpp v39, v35 row_ror:8 row_mask:0xf bank_mask:0xc
	v_mov_b32_dpp v34, v176 quad_perm:[0,1,2,3] row_mask:0xf bank_mask:0x3
	v_mov_b32_dpp v35, v177 quad_perm:[0,1,2,3] row_mask:0xf bank_mask:0x3
;     __device__ __forceinline__ void operator()(const f32x4 (&acc)[2][2][4][2], const Unit& u, int wr, int wc, int fr, int fq, LAS unsigned char*) const {
;     ...
;             for (int m = 0; m < 4; ++m) { const size_t ro = (size_t)(row0 + ai * HALF + m * 16) * ldc + col0;
; #pragma unroll
;                 for (int bj = 0; bj < 2; ++bj) { const size_t o = ro + bj * HALF; const f32x4 r0 = *(const f32x4*)(res + o), r1 = *(const f32x4*)(res + o + 4);
;                     *(f32x4*)(O + o) = r0 + acc[ai][bj][m][0]; *(f32x4*)(O + o + 4) = r1 + acc[ai][bj][m][1]; } }
	v_mov_b32_dpp v176, v28 row_ror:8 row_mask:0xf bank_mask:0xf
	v_mov_b32_dpp v177, v29 row_ror:8 row_mask:0xf bank_mask:0xf
	v_mov_b32_dpp v28, v24 row_ror:8 row_mask:0xf bank_mask:0xc
	v_mov_b32_dpp v29, v25 row_ror:8 row_mask:0xf bank_mask:0xc
	v_mov_b32_dpp v24, v176 quad_perm:[0,1,2,3] row_mask:0xf bank_mask:0x3
	v_mov_b32_dpp v25, v177 quad_perm:[0,1,2,3] row_mask:0xf bank_mask:0x3
	v_mov_b32_dpp v176, v30 row_ror:8 row_mask:0xf bank_mask:0xf
	v_mov_b32_dpp v177, v31 row_ror:8 row_mask:0xf bank_mask:0xf
	v_mov_b32_dpp v30, v26 row_ror:8 row_mask:0xf bank_mask:0xc
	v_mov_b32_dpp v31, v27 row_ror:8 row_mask:0xf bank_mask:0xc
	v_mov_b32_dpp v26, v176 quad_perm:[0,1,2,3] row_mask:0xf bank_mask:0x3
	v_mov_b32_dpp v27, v177 quad_perm:[0,1,2,3] row_mask:0xf bank_mask:0x3
	v_mov_b32_dpp v176, v20 row_ror:8 row_mask:0xf bank_mask:0xf
	v_mov_b32_dpp v177, v21 row_ror:8 row_mask:0xf bank_mask:0xf
	v_mov_b32_dpp v20, v16 row_ror:8 row_mask:0xf bank_mask:0xc
	v_mov_b32_dpp v21, v17 row_ror:8 row_mask:0xf bank_mask:0xc
	v_mov_b32_dpp v16, v176 quad_perm:[0,1,2,3] row_mask:0xf bank_mask:0x3
	v_mov_b32_dpp v17, v177 quad_perm:[0,1,2,3] row_mask:0xf bank_mask:0x3
	v_mov_b32_dpp v176, v22 row_ror:8 row_mask:0xf bank_mask:0xf
	v_mov_b32_dpp v177, v23 row_ror:8 row_mask:0xf bank_mask:0xf
	v_mov_b32_dpp v22, v18 row_ror:8 row_mask:0xf bank_mask:0xc
	v_mov_b32_dpp v23, v19 row_ror:8 row_mask:0xf bank_mask:0xc
	v_mov_b32_dpp v18, v176 quad_perm:[0,1,2,3] row_mask:0xf bank_mask:0x3
	v_mov_b32_dpp v19, v177 quad_perm:[0,1,2,3] row_mask:0xf bank_mask:0x3
	v_mov_b32_dpp v176, v12 row_ror:8 row_mask:0xf bank_mask:0xf
	v_mov_b32_dpp v177, v13 row_ror:8 row_mask:0xf bank_mask:0xf
	v_mov_b32_dpp v12, v8 row_ror:8 row_mask:0xf bank_mask:0xc
	v_mov_b32_dpp v13, v9 row_ror:8 row_mask:0xf bank_mask:0xc
	v_mov_b32_dpp v8, v176 quad_perm:[0,1,2,3] row_mask:0xf bank_mask:0x3
	v_mov_b32_dpp v9, v177 quad_perm:[0,1,2,3] row_mask:0xf bank_mask:0x3
	v_mov_b32_dpp v176, v14 row_ror:8 row_mask:0xf bank_mask:0xf
	v_mov_b32_dpp v177, v15 row_ror:8 row_mask:0xf bank_mask:0xf
	v_mov_b32_dpp v14, v10 row_ror:8 row_mask:0xf bank_mask:0xc
	v_mov_b32_dpp v15, v11 row_ror:8 row_mask:0xf bank_mask:0xc
	v_mov_b32_dpp v10, v176 quad_perm:[0,1,2,3] row_mask:0xf bank_mask:0x3
	v_mov_b32_dpp v11, v177 quad_perm:[0,1,2,3] row_mask:0xf bank_mask:0x3
	v_mov_b32_dpp v176, v4 row_ror:8 row_mask:0xf bank_mask:0xf
	v_mov_b32_dpp v177, v5 row_ror:8 row_mask:0xf bank_mask:0xf
	v_mov_b32_dpp v4, v0 row_ror:8 row_mask:0xf bank_mask:0xc
	v_mov_b32_dpp v5, v1 row_ror:8 row_mask:0xf bank_mask:0xc
	v_mov_b32_dpp v0, v176 quad_perm:[0,1,2,3] row_mask:0xf bank_mask:0x3
	v_mov_b32_dpp v1, v177 quad_perm:[0,1,2,3] row_mask:0xf bank_mask:0x3
	v_mov_b32_dpp v176, v6 row_ror:8 row_mask:0xf bank_mask:0xf
	v_mov_b32_dpp v177, v7 row_ror:8 row_mask:0xf bank_mask:0xf
	v_mov_b32_dpp v6, v2 row_ror:8 row_mask:0xf bank_mask:0xc
	v_mov_b32_dpp v7, v3 row_ror:8 row_mask:0xf bank_mask:0xc
	v_mov_b32_dpp v2, v176 quad_perm:[0,1,2,3] row_mask:0xf bank_mask:0x3
	v_mov_b32_dpp v3, v177 quad_perm:[0,1,2,3] row_mask:0xf bank_mask:0x3
	s_waitcnt vmcnt(12)
	v_pk_add_f32 v[124:125], v[124:125], v[196:197]
	v_pk_add_f32 v[126:127], v[126:127], v[198:199]
	v_pk_add_f32 v[120:121], v[120:121], v[204:205]
	v_pk_add_f32 v[122:123], v[122:123], v[206:207]
	v_pk_add_f32 v[116:117], v[116:117], v[200:201]
	v_pk_add_f32 v[118:119], v[118:119], v[202:203]
	v_pk_add_f32 v[112:113], v[112:113], v[208:209]
	v_pk_add_f32 v[114:115], v[114:115], v[210:211]
	global_store_dwordx4 v[162:163], v[124:127], off
	global_store_dwordx4 v[162:163], v[116:119], off offset:512
	global_store_dwordx4 v[164:165], v[120:123], off
	global_store_dwordx4 v[164:165], v[112:115], off offset:512
	global_load_dwordx4 v[196:199], v[138:139], off
	global_load_dwordx4 v[200:203], v[138:139], off offset:512
	global_load_dwordx4 v[204:207], v[160:161], off
	global_load_dwordx4 v[208:211], v[160:161], off offset:512
	v_lshl_add_u64 v[138:139], v[138:139], 0, s[18:19]
	v_lshl_add_u64 v[160:161], v[160:161], 0, s[18:19]
	v_lshl_add_u64 v[162:163], v[162:163], 0, s[18:19]
	v_lshl_add_u64 v[164:165], v[164:165], 0, s[18:19]
	s_waitcnt vmcnt(16)
	v_pk_add_f32 v[108:109], v[108:109], v[212:213]
	v_pk_add_f32 v[110:111], v[110:111], v[214:215]
	v_pk_add_f32 v[104:105], v[104:105], v[220:221]
	v_pk_add_f32 v[106:107], v[106:107], v[222:223]
	v_pk_add_f32 v[92:93], v[92:93], v[216:217]
	v_pk_add_f32 v[94:95], v[94:95], v[218:219]
	v_pk_add_f32 v[88:89], v[88:89], v[224:225]
	v_pk_add_f32 v[90:91], v[90:91], v[226:227]
	global_store_dwordx4 v[162:163], v[108:111], off
	global_store_dwordx4 v[162:163], v[92:95], off offset:512
	global_store_dwordx4 v[164:165], v[104:107], off
	global_store_dwordx4 v[164:165], v[88:91], off offset:512
	global_load_dwordx4 v[212:215], v[138:139], off
	global_load_dwordx4 v[216:219], v[138:139], off offset:512
	global_load_dwordx4 v[220:223], v[160:161], off
	global_load_dwordx4 v[224:227], v[160:161], off offset:512
	v_lshl_add_u64 v[138:139], v[138:139], 0, s[18:19]
	v_lshl_add_u64 v[160:161], v[160:161], 0, s[18:19]
	v_lshl_add_u64 v[162:163], v[162:163], 0, s[18:19]
	v_lshl_add_u64 v[164:165], v[164:165], 0, s[18:19]
	s_waitcnt vmcnt(20)
;     __device__ __forceinline__ void operator()(const f32x4 (&acc)[2][2][4][2], const Unit& u, int wr, int wc, int fr, int fq, LAS unsigned char*) const {
;     ...
;             for (int m = 0; m < 4; ++m) { const size_t ro = (size_t)(row0 + ai * HALF + m * 16) * ldc + col0;
; #pragma unroll
;                 for (int bj = 0; bj < 2; ++bj) { const size_t o = ro + bj * HALF; const f32x4 r0 = *(const f32x4*)(res + o), r1 = *(const f32x4*)(res + o + 4);
;                     *(f32x4*)(O + o) = r0 + acc[ai][bj][m][0]; *(f32x4*)(O + o + 4) = r1 + acc[ai][bj][m][1]; } }
	v_pk_add_f32 v[100:101], v[100:101], v[228:229]
	v_pk_add_f32 v[102:103], v[102:103], v[230:231]
	v_pk_add_f32 v[96:97], v[96:97], v[236:237]
	v_pk_add_f32 v[98:99], v[98:99], v[238:239]
	v_pk_add_f32 v[76:77], v[76:77], v[232:233]
	v_pk_add_f32 v[78:79], v[78:79], v[234:235]
	v_pk_add_f32 v[72:73], v[72:73], v[240:241]
	v_pk_add_f32 v[74:75], v[74:75], v[242:243]
	global_store_dwordx4 v[162:163], v[100:103], off
	global_store_dwordx4 v[162:163], v[76:79], off offset:512
	global_store_dwordx4 v[164:165], v[96:99], off
	global_store_dwordx4 v[164:165], v[72:75], off offset:512
	global_load_dwordx4 v[228:231], v[138:139], off
	global_load_dwordx4 v[232:235], v[138:139], off offset:512
	global_load_dwordx4 v[236:239], v[160:161], off
	global_load_dwordx4 v[240:243], v[160:161], off offset:512
	v_lshl_add_u64 v[138:139], v[138:139], 0, s[18:19]
	v_lshl_add_u64 v[160:161], v[160:161], 0, s[18:19]
	v_lshl_add_u64 v[162:163], v[162:163], 0, s[18:19]
	v_lshl_add_u64 v[164:165], v[164:165], 0, s[18:19]
	s_waitcnt vmcnt(24)
	v_pk_add_f32 v[84:85], v[84:85], v[168:169]
	v_pk_add_f32 v[86:87], v[86:87], v[170:171]
	v_pk_add_f32 v[80:81], v[80:81], v[180:181]
	v_pk_add_f32 v[82:83], v[82:83], v[182:183]
	v_pk_add_f32 v[68:69], v[68:69], v[172:173]
	v_pk_add_f32 v[70:71], v[70:71], v[174:175]
	v_pk_add_f32 v[64:65], v[64:65], v[156:157]
	v_pk_add_f32 v[66:67], v[66:67], v[158:159]
	global_store_dwordx4 v[162:163], v[84:87], off
	global_store_dwordx4 v[162:163], v[68:71], off offset:512
	global_store_dwordx4 v[164:165], v[80:83], off
	global_store_dwordx4 v[164:165], v[64:67], off offset:512
	global_load_dwordx4 v[168:171], v[138:139], off
	global_load_dwordx4 v[172:175], v[138:139], off offset:512
	global_load_dwordx4 v[180:183], v[160:161], off
	global_load_dwordx4 v[156:159], v[160:161], off offset:512
	v_lshl_add_u64 v[162:163], v[162:163], 0, s[40:41]
	v_lshl_add_u64 v[164:165], v[164:165], 0, s[40:41]
	s_waitcnt vmcnt(24)
	v_pk_add_f32 v[60:61], v[60:61], v[196:197]
	v_pk_add_f32 v[62:63], v[62:63], v[198:199]
	v_pk_add_f32 v[56:57], v[56:57], v[204:205]
	v_pk_add_f32 v[58:59], v[58:59], v[206:207]
	v_pk_add_f32 v[52:53], v[52:53], v[200:201]
	v_pk_add_f32 v[54:55], v[54:55], v[202:203]
	v_pk_add_f32 v[48:49], v[48:49], v[208:209]
	v_pk_add_f32 v[50:51], v[50:51], v[210:211]
	global_store_dwordx4 v[162:163], v[60:63], off
	global_store_dwordx4 v[162:163], v[52:55], off offset:512
	global_store_dwordx4 v[164:165], v[56:59], off
	global_store_dwordx4 v[164:165], v[48:51], off offset:512
	v_lshl_add_u64 v[162:163], v[162:163], 0, s[18:19]
	v_lshl_add_u64 v[164:165], v[164:165], 0, s[18:19]
	s_waitcnt vmcnt(20)
	v_pk_add_f32 v[44:45], v[44:45], v[212:213]
	v_pk_add_f32 v[46:47], v[46:47], v[214:215]
	v_pk_add_f32 v[40:41], v[40:41], v[220:221]
	v_pk_add_f32 v[42:43], v[42:43], v[222:223]
	v_pk_add_f32 v[36:37], v[36:37], v[216:217]
	v_pk_add_f32 v[38:39], v[38:39], v[218:219]
	v_pk_add_f32 v[32:33], v[32:33], v[224:225]
	v_pk_add_f32 v[34:35], v[34:35], v[226:227]
	global_store_dwordx4 v[162:163], v[44:47], off
	global_store_dwordx4 v[162:163], v[36:39], off offset:512
	global_store_dwordx4 v[164:165], v[40:43], off
	global_store_dwordx4 v[164:165], v[32:35], off offset:512
	v_lshl_add_u64 v[162:163], v[162:163], 0, s[18:19]
	v_lshl_add_u64 v[164:165], v[164:165], 0, s[18:19]
	s_waitcnt vmcnt(16)
	v_pk_add_f32 v[28:29], v[28:29], v[228:229]
	v_pk_add_f32 v[30:31], v[30:31], v[230:231]
	v_pk_add_f32 v[24:25], v[24:25], v[236:237]
	v_pk_add_f32 v[26:27], v[26:27], v[238:239]
	v_pk_add_f32 v[20:21], v[20:21], v[232:233]
	v_pk_add_f32 v[22:23], v[22:23], v[234:235]
	v_pk_add_f32 v[16:17], v[16:17], v[240:241]
	v_pk_add_f32 v[18:19], v[18:19], v[242:243]
	global_store_dwordx4 v[162:163], v[28:31], off
	global_store_dwordx4 v[162:163], v[20:23], off offset:512
	global_store_dwordx4 v[164:165], v[24:27], off
	global_store_dwordx4 v[164:165], v[16:19], off offset:512
	v_lshl_add_u64 v[162:163], v[162:163], 0, s[18:19]
	v_lshl_add_u64 v[164:165], v[164:165], 0, s[18:19]
	s_waitcnt vmcnt(12)
	v_pk_add_f32 v[12:13], v[12:13], v[168:169]
	v_pk_add_f32 v[14:15], v[14:15], v[170:171]
	v_pk_add_f32 v[8:9], v[8:9], v[180:181]
	v_pk_add_f32 v[10:11], v[10:11], v[182:183]
	v_pk_add_f32 v[4:5], v[4:5], v[172:173]
	v_pk_add_f32 v[6:7], v[6:7], v[174:175]
	v_pk_add_f32 v[0:1], v[0:1], v[156:157]
	v_pk_add_f32 v[2:3], v[2:3], v[158:159]
	global_store_dwordx4 v[162:163], v[12:15], off
	global_store_dwordx4 v[162:163], v[4:7], off offset:512
	global_store_dwordx4 v[164:165], v[8:11], off
	global_store_dwordx4 v[164:165], v[0:3], off offset:512
	s_mov_b64 s[14:15], -1
	s_and_b64 vcc, exec, s[44:45]
	s_cbranch_vccnz .LBB0_749
	s_andn2_b64 vcc, exec, s[52:53]
	s_cbranch_vccnz .LBB0_748
	s_barrier
	s_branch .LBB0_748
